# D5: next query row's index list prefetched one row ahead
# baseline (speedup 1.0000x reference)
; __device__ __forceinline__ int opaque_tid() { int t = threadIdx.x; asm volatile("" : "+v"(t)); return t; }
; __device__ __forceinline__ void dsa_attn_phase(const Params& p, int j, unsigned char* smem) {
;     const int tid = opaque_tid(), wave = tid >> 6, lane = tid & 63, r = lane & 15, q = lane >> 4;
;     float* BL = (float*)(smem + SA_BL);
;     for (int idx = tid; idx < 16 * 129; idx += 512) {
;         const int h = idx / 129, d = idx % 129;
;         int bk = d;
;         if (d >= 16) { bk = 16 + (int)(logf((float)d * (1.0f / 16.0f)) / 2.0794415416798357f * 16.0f); bk = bk > 31 ? 31 : bk; }
;         BL[h * 132 + d] = p.in[32][bk * 16 + h] * 1.4426950408889634f;
;     }
;     __syncthreads();
;     const h16* qabs = (const h16*)(p.ws + D_QABS);
;     const h16* ckv = (const h16*)(p.ws + D_CKV);
;     const unsigned short* sel = (const unsigned short*)(p.ws + D_MASK);
;     h16* olatA = (h16*)(p.ws + D_HIN);
;     h16* olatB = (h16*)p.out + (size_t)MTOK * 1024;
;     unsigned char* tile0 = smem + wave * (2 * SA_TILE);
;     const float NINF = -__builtin_inff();
;     unsigned wofs[8], kofs[2][4], vofs[8][2];
; #pragma unroll
;     for (int i = 0; i < 8; ++i) wofs[i] = off_b(8 * q + i, r);
; #pragma unroll
;     for (int tt = 0; tt < 2; ++tt)
; #pragma unroll
;         for (int kk = 0; kk < 4; ++kk) kofs[tt][kk] = off_b(8 * (r >> 2) + 4 * tt + (r & 3), 4 * kk + q);
; #pragma unroll
;     for (int c = 0; c < 8; ++c)
; #pragma unroll
;         for (int t2 = 0; t2 < 2; ++t2) vofs[c][t2] = off_b(8 * q + 4 * t2 + (r >> 2), 2 * c + ((lane & 3) >> 1)) + 8 * (lane & 1);
.LBB0_92:
	s_or_b64 exec, exec, s[2:3]
	v_ashrrev_i32_e32 v1, 6, v0
	v_readlane_b32 s0, v250, 23
	s_waitcnt lgkmcnt(0)
	s_barrier
	v_add_u32_e32 v128, s0, v1
	s_mov_b32 s0, 0x10000
	v_cmp_gt_i32_e32 vcc, s0, v128
	s_and_saveexec_b64 s[0:1], vcc
	s_cbranch_execz .LBB0_105
	v_bfe_u32 v5, v0, 4, 2
	v_lshlrev_b32_e32 v2, 3, v5
	v_or_b32_e32 v3, 4, v2
	v_bfe_u32 v10, v0, 1, 1
	s_waitcnt vmcnt(0)
	v_lshrrev_b32_e32 v16, 3, v0
	v_bfe_u32 v7, v3, 2, 2
	v_and_b32_e32 v8, 12, v0
	v_or_b32_e32 v11, 14, v10
	v_bfe_u32 v13, v0, 2, 2
	v_and_b32_e32 v17, 2, v16
	v_or_b32_e32 v18, 12, v10
	v_or_b32_e32 v20, 10, v10
	v_or_b32_e32 v22, 8, v10
	v_or_b32_e32 v24, 6, v10
	v_or_b32_e32 v26, 4, v10
	v_or_b32_e32 v28, 2, v10
	v_bitop3_b32 v12, v7, v11, v8 bitop3:0x36
	v_or_b32_e32 v14, v3, v13
	v_lshlrev_b32_e32 v15, 3, v0
	v_bitop3_b32 v11, v17, v11, v8 bitop3:0x36
	v_or_b32_e32 v13, v2, v13
	v_bitop3_b32 v19, v7, v18, v8 bitop3:0x36
	v_bitop3_b32 v18, v17, v18, v8 bitop3:0x36
	v_bitop3_b32 v21, v7, v20, v8 bitop3:0x36
	v_bitop3_b32 v20, v17, v20, v8 bitop3:0x36
	v_bitop3_b32 v23, v7, v22, v8 bitop3:0x36
	v_bitop3_b32 v22, v17, v22, v8 bitop3:0x36
	v_bitop3_b32 v25, v7, v24, v8 bitop3:0x36
	v_bitop3_b32 v24, v17, v24, v8 bitop3:0x36
	v_bitop3_b32 v27, v7, v26, v8 bitop3:0x36
	v_bitop3_b32 v26, v17, v26, v8 bitop3:0x36
	v_bitop3_b32 v29, v7, v28, v8 bitop3:0x36
	v_bitop3_b32 v28, v17, v28, v8 bitop3:0x36
	v_bitop3_b32 v7, v7, v10, v8 bitop3:0x36
	v_or3_b32 v8, v17, v8, v10
	v_and_b32_e32 v15, 8, v15
	v_lshlrev_b32_e32 v11, 4, v11
	v_lshlrev_b32_e32 v13, 8, v13
	v_lshlrev_b32_e32 v18, 4, v18
	v_lshlrev_b32_e32 v20, 4, v20
	v_lshlrev_b32_e32 v22, 4, v22
	v_lshlrev_b32_e32 v24, 4, v24
	v_lshlrev_b32_e32 v26, 4, v26
	v_lshlrev_b32_e32 v28, 4, v28
	v_lshlrev_b32_e32 v8, 4, v8
	v_or3_b32 v11, v11, v13, v15
	v_or3_b32 v18, v18, v13, v15
	v_or3_b32 v20, v20, v13, v15
	v_or3_b32 v22, v22, v13, v15
	v_or3_b32 v24, v24, v13, v15
	v_or3_b32 v26, v26, v13, v15
	v_or3_b32 v28, v28, v13, v15
	v_or3_b32 v8, v8, v13, v15
	v_lshlrev_b32_e32 v13, 1, v0
	v_lshlrev_b32_e32 v12, 4, v12
	v_lshlrev_b32_e32 v14, 8, v14
	v_lshlrev_b32_e32 v19, 4, v19
	v_lshlrev_b32_e32 v21, 4, v21
	v_lshlrev_b32_e32 v23, 4, v23
	v_lshlrev_b32_e32 v25, 4, v25
	v_lshlrev_b32_e32 v27, 4, v27
	v_lshlrev_b32_e32 v29, 4, v29
	v_lshlrev_b32_e32 v7, 4, v7
	v_and_b32_e32 v13, 24, v13
	v_and_b32_e32 v4, 15, v0
	v_lshrrev_b32_e32 v9, 1, v0
	v_or3_b32 v12, v12, v14, v15
	v_or3_b32 v19, v19, v14, v15
	v_or3_b32 v21, v21, v14, v15
	v_or3_b32 v23, v23, v14, v15
	v_or3_b32 v25, v25, v14, v15
	v_or3_b32 v27, v27, v14, v15
	v_or3_b32 v29, v29, v14, v15
	v_or3_b32 v7, v7, v14, v15
	v_or_b32_e32 v14, 4, v13
	v_and_b32_e32 v0, 3, v0
	v_or_b32_e32 v10, 12, v5
	v_bfe_u32 v15, v14, 2, 2
	v_lshlrev_b32_e32 v30, 2, v0
	v_or_b32_e32 v14, v14, v0
	v_or_b32_e32 v31, 8, v5
	v_or_b32_e32 v32, 4, v5
	v_bitop3_b32 v10, v15, v10, v30 bitop3:0x36
	v_lshlrev_b32_e32 v14, 8, v14
	v_bitop3_b32 v31, v15, v31, v30 bitop3:0x36
	v_bitop3_b32 v32, v15, v32, v30 bitop3:0x36
	v_bitop3_b32 v15, v15, v5, v30 bitop3:0x36
	v_and_b32_e32 v9, 2, v9
	v_lshl_or_b32 v10, v10, 4, v14
	v_lshl_or_b32 v31, v31, 4, v14
	v_lshl_or_b32 v32, v32, 4, v14
	v_lshl_or_b32 v14, v15, 4, v14
	v_or_b32_e32 v15, v9, v30
	v_or_b32_e32 v0, v13, v0
	v_bitop3_b32 v33, v5, v15, 12 bitop3:0x36
	v_lshlrev_b32_e32 v0, 8, v0
	v_lshl_or_b32 v13, v33, 4, v0
	v_bitop3_b32 v33, v5, v15, 8 bitop3:0x36
	v_bitop3_b32 v15, v5, v15, 4 bitop3:0x36
	v_bitop3_b32 v9, v9, v5, v30 bitop3:0x36
	v_lshl_or_b32 v33, v33, 4, v0
	v_lshl_or_b32 v15, v15, 4, v0
	v_lshl_or_b32 v9, v9, 4, v0
	v_or_b32_e32 v0, 7, v2
	v_lshrrev_b32_e32 v30, 2, v0
	v_bitop3_b32 v30, v30, v4, 12 bitop3:0x36
	v_lshlrev_b32_e32 v0, 8, v0
	v_lshl_add_u32 v30, v30, 4, v0
	v_or_b32_e32 v0, 6, v2
	v_bfe_u32 v34, v0, 2, 2
	v_bitop3_b32 v34, v34, v4, 8 bitop3:0x36
	v_lshlrev_b32_e32 v0, 8, v0
	v_lshl_or_b32 v34, v34, 4, v0
	v_or_b32_e32 v0, 5, v2
	v_lshrrev_b32_e32 v2, 2, v0
	v_lshrrev_b32_e32 v6, 2, v3
	v_bitop3_b32 v2, v2, v4, 4 bitop3:0x36
	v_lshlrev_b32_e32 v0, 8, v0
	v_readlane_b32 s2, v250, 26
	v_lshl_add_u32 v35, v2, 4, v0
	v_bitop3_b32 v0, v6, v4, 3 bitop3:0x6c
	v_lshlrev_b32_e32 v2, 8, v3
	v_lshlrev_b32_e32 v196, 8, v4
	v_readlane_b32 s3, v250, 27
	v_lshl_or_b32 v6, v0, 4, v2
	v_lshlrev_b32_e32 v37, 11, v5
	v_lshl_add_u64 v[2:3], s[2:3], 0, v[196:197]
	v_lshlrev_b32_e32 v196, 4, v5
	v_bitop3_b32 v0, v16, v4, 2 bitop3:0x6c
	v_lshl_add_u64 v[130:131], v[2:3], 0, v[196:197]
	v_mov_b32_e32 v2, s57
	v_readlane_b32 s2, v250, 24
	v_bitop3_b32 v36, v17, v4, 12 bitop3:0x36
	v_bitop3_b32 v38, v17, v4, 8 bitop3:0x36
	v_bitop3_b32 v17, v17, v4, 4 bitop3:0x36
	v_lshl_or_b32 v16, v0, 4, v37
	v_lshlrev_b32_e32 v0, 7, v4
	v_mad_u32_u24 v148, v4, s82, v2
	v_lshlrev_b32_e32 v2, 2, v5
	v_lshlrev_b32_e32 v4, 4, v4
	v_mov_b32_e32 v5, v197
	v_readlane_b32 s3, v250, 25
	v_lshl_add_u32 v1, v1, 14, 0
	v_lshl_or_b32 v3, v17, 4, v37
	v_lshl_add_u64 v[132:133], s[2:3], 0, v[4:5]
	v_readlane_b32 s2, v250, 21
	v_readlane_b32 s3, v250, 22
	v_lshl_or_b32 v4, v38, 4, v37
	v_lshl_or_b32 v5, v36, 4, v37
	v_lshl_add_u64 v[134:135], s[2:3], 0, v[196:197]
	v_readlane_b32 s2, v251, 23
	v_readlane_b32 s3, v251, 24
	v_lshlrev_b32_e32 v138, 1, v0
	v_lshlrev_b32_e32 v140, 1, v2
	v_lshl_add_u64 v[136:137], s[2:3], 0, v[196:197]
	s_mov_b64 s[2:3], 0
	v_add_u32_e32 v149, v1, v16
	v_add_u32_e32 v150, v1, v3
	v_add_u32_e32 v151, v1, v4
	v_add_u32_e32 v152, v1, v5
	v_add_u32_e32 v153, v1, v6
	v_add_u32_e32 v154, v1, v35
	v_add_u32_e32 v155, v1, v34
	v_add_u32_e32 v156, v1, v30
	v_add_u32_e32 v157, v1, v9
	v_add_u32_e32 v158, v1, v15
	v_add_u32_e32 v159, v1, v33
	v_add_u32_e32 v160, v1, v13
	v_add_u32_e32 v161, v1, v14
	v_add_u32_e32 v162, v1, v32
	v_add_u32_e32 v163, v1, v31
	v_add_u32_e32 v164, v1, v10
	v_add_u32_e32 v165, v1, v8
	v_add_u32_e32 v166, v1, v7
	v_add_u32_e32 v167, v1, v28
	v_add_u32_e32 v168, v1, v29
	v_add_u32_e32 v169, v1, v26
	v_add_u32_e32 v170, v1, v27
	v_add_u32_e32 v171, v1, v24
	v_add_u32_e32 v172, v1, v25
	v_add_u32_e32 v173, v1, v22
	v_add_u32_e32 v174, v1, v23
	v_add_u32_e32 v175, v1, v20
	v_add_u32_e32 v176, v1, v21
	v_add_u32_e32 v177, v1, v18
	v_add_u32_e32 v178, v1, v19
	v_add_u32_e32 v179, v1, v11
	v_add_u32_e32 v180, v1, v12
	v_readfirstlane_b32 s14, v134
	v_readfirstlane_b32 s15, v135
	v_and_b32_e32 v240, 63, v226
	v_lshlrev_b32_e32 v240, 3, v240
	v_lshl_add_u32 v239, v128, 9, v240
	s_nop 2
	global_load_dwordx2 v[146:147], v239, s[14:15]
	s_waitcnt vmcnt(0)
	s_branch .LBB0_95

; #define SA_GATHER(GR, SELV) do { _Pragma("unroll") for (int i = 0; i < 8; ++i) { \
;             unsigned sidx = ((SELV)[i >> 1] >> ((i & 1) * 16)) & 0xFFFFu; sidx = sidx == 0xFFFFu ? 0u : sidx; \
;             (GR)[i] = *(const u32x4*)(kg + (size_t)sidx * 128 + r * 8); } } while (0)
; __device__ __forceinline__ void dsa_attn_phase(const Params& p, int j, unsigned char* smem) {
;     ...
;     for (int row = blockIdx.x * 8 + wave; row < MTOK; row += gridDim.x * 8) {
;         const int b = row >> 11, t = row & 2047;
;         const int nvalid = t + 1 < 256 ? t + 1 : 256, ng = (nvalid + 31) >> 5;
;         const h16* kg = ckv + (size_t)(b * 2048) * 128;
;         const unsigned short* srow = sel + (size_t)row * 256;
;         h16x8 qf[4];
; #pragma unroll
;         for (int kk = 0; kk < 4; ++kk) qf[kk] = *(const h16x8*)(qabs + (size_t)row * 2048 + r * 128 + kk * 32 + q * 8);
;         f32x4 O[8];
; #pragma unroll
;         for (int dt = 0; dt < 8; ++dt) O[dt] = (f32x4){0.f, 0.f, 0.f, 0.f};
;         float mrun = NINF, lrun = 0.f;
;         u32x4 selA = *(const u32x4*)(srow + 8 * q), selB = selA;
;         u32x4 grA[8], grB[8];
;     ...
;         SA_GATHER(grA, selA);
;         if (ng > 1) { selB = *(const u32x4*)(srow + 32 + 8 * q); SA_GATHER(grB, selB); }
.LBB0_95:
	v_ashrrev_i32_e32 v129, 31, v128
	v_lshlrev_b64 v[72:73], 9, v[128:129]
	v_lshl_add_u64 v[74:75], v[134:135], 0, v[72:73]
	s_waitcnt vmcnt(8)
	v_lshlrev_b32_e32 v240, 3, v226
	v_add_u32_e32 v240, 0x22100, v240
	ds_write_b64 v240, v[146:147]
	v_and_b32_e32 v0, 0xfffff800, v128
	v_ashrrev_i32_e32 v1, 31, v0
	v_lshlrev_b64 v[46:47], 8, v[0:1]
	v_lshl_add_u64 v[144:145], v[132:133], 0, v[46:47]
	v_lshlrev_b64 v[142:143], 12, v[128:129]
	v_lshl_add_u64 v[44:45], v[130:131], 0, v[142:143]
	v_readfirstlane_b32 s12, v144
	v_readfirstlane_b32 s13, v145
	v_and_b32_e32 v192, 15, v226
	v_lshlrev_b32_e32 v192, 4, v192
	global_load_dwordx4 v[0:3], v[44:45], off
	global_load_dwordx4 v[4:7], v[44:45], off offset:64
	global_load_dwordx4 v[8:11], v[44:45], off offset:128
	v_and_b32_e32 v129, 0x7ff, v128
	v_lshrrev_b32_e32 v238, 6, v226
	v_lshlrev_b32_e32 v238, 9, v238
	v_bfe_u32 v239, v226, 4, 2
	v_lshl_add_u32 v238, v239, 4, v238
	v_add_u32_e32 v238, 0x22100, v238
	v_readlane_b32 s16, v250, 28
	v_and_b32_e32 v240, 63, v226
	v_lshlrev_b32_e32 v240, 3, v240
	v_add_u32_e32 v239, s16, v128
	v_lshl_add_u32 v239, v239, 9, v240
	s_waitcnt lgkmcnt(0)
	global_load_dwordx2 v[146:147], v239, s[14:15]
	v_readfirstlane_b32 s17, v129
	ds_read_b32 v241, v148 offset:512
	s_sub_i32 s17, s17, 0x80
	ds_read_b128 v[120:123], v238
	s_waitcnt lgkmcnt(0)
	v_bfe_u32 v48, v120, 0, 11
	v_bfe_u32 v52, v120, 16, 11
	v_bfe_u32 v56, v121, 0, 11
	v_bfe_u32 v60, v121, 16, 11
	v_bfe_u32 v64, v122, 0, 11
	v_bfe_u32 v68, v122, 16, 11
	v_bfe_u32 v76, v123, 0, 11
	v_bfe_u32 v88, v123, 16, 11
	v_lshl_add_u32 v48, v48, 8, v192
	v_lshl_add_u32 v52, v52, 8, v192
	v_lshl_add_u32 v56, v56, 8, v192
	v_lshl_add_u32 v60, v60, 8, v192
	v_lshl_add_u32 v64, v64, 8, v192
	v_lshl_add_u32 v68, v68, 8, v192
	v_lshl_add_u32 v76, v76, 8, v192
	v_lshl_add_u32 v88, v88, 8, v192
	v_mov_b64_e32 v[116:117], v[120:121]
	v_mov_b64_e32 v[118:119], v[122:123]
	global_load_dwordx4 v[44:47], v[44:45], off offset:192
	global_load_dwordx4 v[48:51], v48, s[12:13]
	s_nop 0
	global_load_dwordx4 v[52:55], v52, s[12:13]
	s_nop 0
	global_load_dwordx4 v[56:59], v56, s[12:13]
	s_nop 0
	global_load_dwordx4 v[60:63], v60, s[12:13]
	s_nop 0
	global_load_dwordx4 v[64:67], v64, s[12:13]
	s_nop 0
	global_load_dwordx4 v[68:71], v68, s[12:13]
	s_nop 0
	global_load_dwordx4 v[76:79], v76, s[12:13]
	v_cmp_lt_u32_e32 vcc, 31, v129
	s_nop 0
	global_load_dwordx4 v[88:91], v88, s[12:13]
	s_and_saveexec_b64 s[4:5], vcc
	s_cbranch_execz .LBB0_97
	ds_read_b128 v[116:119], v238 offset:64
	s_waitcnt lgkmcnt(0)
	v_bfe_u32 v12, v116, 0, 11
	v_bfe_u32 v16, v116, 16, 11
	v_bfe_u32 v20, v117, 0, 11
	v_bfe_u32 v24, v117, 16, 11
	v_bfe_u32 v28, v118, 0, 11
	v_bfe_u32 v32, v118, 16, 11
	v_bfe_u32 v36, v119, 0, 11
	v_bfe_u32 v40, v119, 16, 11
	v_lshl_add_u32 v12, v12, 8, v192
	v_lshl_add_u32 v16, v16, 8, v192
	v_lshl_add_u32 v20, v20, 8, v192
	v_lshl_add_u32 v24, v24, 8, v192
	v_lshl_add_u32 v28, v28, 8, v192
	v_lshl_add_u32 v32, v32, 8, v192
	v_lshl_add_u32 v36, v36, 8, v192
	v_lshl_add_u32 v40, v40, 8, v192
	global_load_dwordx4 v[12:15], v12, s[12:13]
	s_nop 0
	global_load_dwordx4 v[16:19], v16, s[12:13]
	s_nop 0
	global_load_dwordx4 v[20:23], v20, s[12:13]
	s_nop 0
	global_load_dwordx4 v[24:27], v24, s[12:13]
	s_nop 0
	global_load_dwordx4 v[28:31], v28, s[12:13]
	s_nop 0
	global_load_dwordx4 v[32:35], v32, s[12:13]
	s_nop 0
	global_load_dwordx4 v[36:39], v36, s[12:13]
	s_nop 0
	global_load_dwordx4 v[40:43], v40, s[12:13]
.LBB0_97:
	s_or_b64 exec, exec, s[4:5]
	v_add_u32_e32 v238, 0x80, v238
	v_min_u32_e32 v72, 0xff, v129
	v_add_u32_e32 v72, 32, v72
	v_mov_b32_e32 v182, 0
	v_mov_b64_e32 v[112:113], v[120:121]
	v_lshrrev_b32_e32 v139, 5, v72
	v_mov_b32_e32 v183, 0xff800000
	s_mov_b32 s10, 3
	s_mov_b64 s[4:5], 0
	v_mov_b32_e32 v108, 0
	v_mov_b32_e32 v109, v182
	v_mov_b32_e32 v110, v182
	v_mov_b32_e32 v111, v182
	v_mov_b32_e32 v104, 0
	v_mov_b32_e32 v105, v182
	v_mov_b32_e32 v106, v182
	v_mov_b32_e32 v107, v182
	v_mov_b32_e32 v100, 0
	v_mov_b32_e32 v101, v182
	v_mov_b32_e32 v102, v182
	v_mov_b32_e32 v103, v182
	v_mov_b32_e32 v96, 0
	v_mov_b32_e32 v97, v182
	v_mov_b32_e32 v98, v182
	v_mov_b32_e32 v99, v182
	v_mov_b32_e32 v92, 0
	v_mov_b32_e32 v93, v182
	v_mov_b32_e32 v94, v182
	v_mov_b32_e32 v95, v182
	v_mov_b32_e32 v84, 0
	v_mov_b32_e32 v85, v182
	v_mov_b32_e32 v86, v182
	v_mov_b32_e32 v87, v182
	v_mov_b32_e32 v72, 0
	v_mov_b32_e32 v73, v182
	v_mov_b32_e32 v74, v182
	v_mov_b32_e32 v75, v182
	v_mov_b32_e32 v80, 0
	v_mov_b32_e32 v81, v182
	v_mov_b32_e32 v82, v182
	v_mov_b32_e32 v83, v182
	v_mov_b64_e32 v[114:115], v[122:123]
	s_branch .LBB0_100

; __device__ __forceinline__ void dsa_attn_phase(const Params& p, int j, unsigned char* smem) {
;     ...
;         for (int g = 0; g < ng; g += 2) {
;             SA_GROUP(grA, selA, g);
;             if (g + 1 < ng) SA_GROUP(grB, selB, g + 1);
;         }
.LBB0_99:
	s_or_b64 exec, exec, s[6:7]
	s_add_i32 s10, s10, 2
	v_cmp_ge_u32_e32 vcc, s11, v139
	v_mov_b64_e32 v[122:123], v[114:115]
	v_add_u32_e32 v238, 0x80, v238
	s_or_b64 s[4:5], vcc, s[4:5]
	v_mov_b32_e32 v183, v181
	v_mov_b32_e32 v182, v141
	v_mov_b64_e32 v[120:121], v[112:113]
	s_andn2_b64 exec, exec, s[4:5]
	s_cbranch_execz .LBB0_94
